# out-proj: the two 128x128 tiles of a workgroup computed as one 256x128 tile with the in-proj style K loop (weights fetched once, 16 MFMAs per barrier), 128x128 epilogue run twice
# speedup vs baseline: 1.0072x; 1.0029x over previous
; DI int otid() { int t = threadIdx.x; asm volatile("" : "+v"(t)); return t; }
; template <bool VMODE, int TJ>
; DI void gemm_mainloop(const bf16_t* __restrict__ W, const bf16_t* __restrict__ X, int NW, char* smem, f32x16 (&acc)[2][TJ]) {
;     constexpr int XROWS = 64 * TJ, STAGE = (128 + XROWS) * 64, NPW = 2 + TJ;
;     const int tid = otid(), lane = tid & 63, wave = tid >> 6, r = lane & 31, h = lane >> 5, wf = wave & 1, wt = wave >> 1;
;     const int goff = (16 * wave + (lane >> 2)) * 32 + (((lane & 3) ^ (lane >> 4)) << 3);
;     const bf16_t* wp = W + goff;
;     const bf16_t* xp = X + goff;
;     const size_t wks = (size_t)NW * 32, xks = (size_t)NTOK * 32;
;     char* ld = smem + tid * 16;
;     ...
;     const int xr = (r >> 2) & 3;
;     const int fo0 = r * 64 + (((0 + h) ^ xr) << 4), fo1 = r * 64 + (((2 + h) ^ xr) << 4);
;     __syncthreads();
; template <int TJ>
; DI void outproj_tile(const Params& p, int l, char* smem, int b, int trow0, int n0) {
;     const int tid = otid(), lane = tid & 63, wave = tid >> 6, r = lane & 31, h = lane >> 5, wf = wave & 1, wt = wave >> 1;
;     const bf16_t* W = p.wtout + (size_t)l * D * D + (size_t)n0 * 32;
;     const bf16_t* X = p.hmix + ((size_t)b * TPB + trow0) * 32;
;     f32x16 acc[2][TJ];
;     zero_acc<TJ>(acc);
;     gemm_mainloop<false, TJ>(W, X, D, smem, acc);
.LBB0_39:
	v_mov_b32_e32 v116, v200
	s_cmp_lg_u32 s6, 0
	s_cbranch_scc1 .Lop4_second
	s_load_dwordx2 s[8:9], s[0:1], 0xd8
	s_load_dwordx2 s[56:57], s[0:1], 0xb8
	s_mov_b64 s[62:63], 0
	v_readlane_b32 s4, v254, 13
	s_nop 0
	s_add_i32 s4, s6, s4
	s_and_b32 s28, s4, 0x7fffff80
	s_waitcnt lgkmcnt(0)
	s_add_u32 s8, s8, s58
	s_addc_u32 s9, s9, s59
	v_readlane_b32 s4, v254, 14
	s_nop 0
	s_add_u32 s4, s8, s4
	s_addc_u32 s5, s9, 0
	v_readlane_b32 s6, v255, 23
	s_nop 0
	s_add_i32 s6, s6, s28
	s_mov_b32 s7, s75
	s_lshl_b64 s[6:7], s[6:7], 6
	s_add_u32 s6, s56, s6
	s_addc_u32 s7, s57, s7
	v_bfe_u32 v1, v200, 4, 2
	v_bitop3_b32 v1, v1, v200, 3 bitop3:0x78
	v_lshlrev_b32_e32 v0, 3, v200
	v_lshlrev_b32_e32 v1, 3, v1
	s_movk_i32 s29, 0xffe0
	v_and_or_b32 v0, v0, s29, v1
	v_lshlrev_b32_e32 v128, 1, v0
	v_lshl_add_u32 v130, v200, 4, 32
	v_bfe_u32 v5, v200, 5, 1
	v_bfe_u32 v7, v200, 2, 2
	v_bitop3_b32 v9, v5, v7, 2 bitop3:0x36
	v_lshrrev_b32_e32 v6, 2, v200
	v_lshlrev_b32_e32 v8, 6, v200
	v_bitop3_b32 v6, v5, v6, 3 bitop3:0x78
	v_and_b32_e32 v10, 0x7c0, v8
	v_lshl_or_b32 v131, v6, 4, v10
	v_lshl_or_b32 v132, v9, 4, v10
	v_and_b32_e32 v134, 0x1000, v8
	v_and_b32_e32 v133, 0xffffe000, v8
	v_mov_b32_e32 v170, v128
	v_add_u32_e32 v171, 0x1000, v128
	v_add_u32_e32 v172, 0x10000, v128
	v_add_u32_e32 v173, 0x11000, v128
	v_readfirstlane_b32 s100, v130
	v_mov_b32_e32 v0, 0
	v_mov_b32_e32 v1, 0
	v_mov_b32_e32 v2, 0
	v_mov_b32_e32 v3, 0
	v_mov_b32_e32 v4, 0
	v_mov_b32_e32 v5, 0
	v_mov_b32_e32 v6, 0
	v_mov_b32_e32 v7, 0
	v_mov_b32_e32 v8, 0
	v_mov_b32_e32 v9, 0
	v_mov_b32_e32 v10, 0
	v_mov_b32_e32 v11, 0
	v_mov_b32_e32 v12, 0
	v_mov_b32_e32 v13, 0
	v_mov_b32_e32 v14, 0
	v_mov_b32_e32 v15, 0
	v_mov_b32_e32 v16, 0
	v_mov_b32_e32 v17, 0
	v_mov_b32_e32 v18, 0
	v_mov_b32_e32 v19, 0
	v_mov_b32_e32 v20, 0
	v_mov_b32_e32 v21, 0
	v_mov_b32_e32 v22, 0
	v_mov_b32_e32 v23, 0
	v_mov_b32_e32 v24, 0
	v_mov_b32_e32 v25, 0
	v_mov_b32_e32 v26, 0
	v_mov_b32_e32 v27, 0
	v_mov_b32_e32 v28, 0
	v_mov_b32_e32 v29, 0
	v_mov_b32_e32 v30, 0
	v_mov_b32_e32 v31, 0
	v_mov_b32_e32 v32, 0
	v_mov_b32_e32 v33, 0
	v_mov_b32_e32 v34, 0
	v_mov_b32_e32 v35, 0
	v_mov_b32_e32 v36, 0
	v_mov_b32_e32 v37, 0
	v_mov_b32_e32 v38, 0
	v_mov_b32_e32 v39, 0
	v_mov_b32_e32 v40, 0
	v_mov_b32_e32 v41, 0
	v_mov_b32_e32 v42, 0
	v_mov_b32_e32 v43, 0
	v_mov_b32_e32 v44, 0
	v_mov_b32_e32 v45, 0
	v_mov_b32_e32 v46, 0
	v_mov_b32_e32 v47, 0
	v_mov_b32_e32 v48, 0
	v_mov_b32_e32 v49, 0
	v_mov_b32_e32 v50, 0
	v_mov_b32_e32 v51, 0
	v_mov_b32_e32 v52, 0
	v_mov_b32_e32 v53, 0
	v_mov_b32_e32 v54, 0
	v_mov_b32_e32 v55, 0
	v_mov_b32_e32 v56, 0
	v_mov_b32_e32 v57, 0
	v_mov_b32_e32 v58, 0
	v_mov_b32_e32 v59, 0
	v_mov_b32_e32 v60, 0
	v_mov_b32_e32 v61, 0
	v_mov_b32_e32 v62, 0
	v_mov_b32_e32 v63, 0
	v_mov_b32_e32 v64, 0
	v_mov_b32_e32 v65, 0
	v_mov_b32_e32 v66, 0
	v_mov_b32_e32 v67, 0
	v_mov_b32_e32 v68, 0
	v_mov_b32_e32 v69, 0
	v_mov_b32_e32 v70, 0
	v_mov_b32_e32 v71, 0
	v_mov_b32_e32 v72, 0
	v_mov_b32_e32 v73, 0
	v_mov_b32_e32 v74, 0
	v_mov_b32_e32 v75, 0
	v_mov_b32_e32 v76, 0
	v_mov_b32_e32 v77, 0
	v_mov_b32_e32 v78, 0
	v_mov_b32_e32 v79, 0
	v_mov_b32_e32 v80, 0
	v_mov_b32_e32 v81, 0
	v_mov_b32_e32 v82, 0
	v_mov_b32_e32 v83, 0
	v_mov_b32_e32 v84, 0
	v_mov_b32_e32 v85, 0
	v_mov_b32_e32 v86, 0
	v_mov_b32_e32 v87, 0
	v_mov_b32_e32 v88, 0
	v_mov_b32_e32 v89, 0
	v_mov_b32_e32 v90, 0
	v_mov_b32_e32 v91, 0
	v_mov_b32_e32 v92, 0
	v_mov_b32_e32 v93, 0
	v_mov_b32_e32 v94, 0
	v_mov_b32_e32 v95, 0
	v_mov_b32_e32 v96, 0
	v_mov_b32_e32 v97, 0
	v_mov_b32_e32 v98, 0
	v_mov_b32_e32 v99, 0
	v_mov_b32_e32 v100, 0
	v_mov_b32_e32 v101, 0
	v_mov_b32_e32 v102, 0
	v_mov_b32_e32 v103, 0
	v_mov_b32_e32 v104, 0
	v_mov_b32_e32 v105, 0
	v_mov_b32_e32 v106, 0
	v_mov_b32_e32 v107, 0
	v_mov_b32_e32 v108, 0
	v_mov_b32_e32 v109, 0
	v_mov_b32_e32 v110, 0
	v_mov_b32_e32 v111, 0
	v_mov_b32_e32 v112, 0
	v_mov_b32_e32 v113, 0
	v_mov_b32_e32 v114, 0
	v_mov_b32_e32 v115, 0
	v_mov_b32_e32 v116, 0
	v_mov_b32_e32 v117, 0
	v_mov_b32_e32 v118, 0
	v_mov_b32_e32 v119, 0
	v_mov_b32_e32 v120, 0
	v_mov_b32_e32 v121, 0
	v_mov_b32_e32 v122, 0
	v_mov_b32_e32 v123, 0
	v_mov_b32_e32 v124, 0
	v_mov_b32_e32 v125, 0
	v_mov_b32_e32 v126, 0
	v_mov_b32_e32 v127, 0
	s_barrier
	s_mov_b32 s101, s100
	s_mov_b32 m0, s101
	s_nop 0
	global_load_lds_dwordx4 v170, s[4:5]
	s_add_u32 m0, s101, 0x1000
	s_nop 0
	global_load_lds_dwordx4 v171, s[4:5]
	s_add_u32 m0, s101, 0x2000
	s_nop 0
	global_load_lds_dwordx4 v172, s[6:7]
	s_add_u32 m0, s101, 0x3000
	s_nop 0
	global_load_lds_dwordx4 v170, s[6:7]
	s_add_u32 m0, s101, 0x4000
	s_nop 0
	global_load_lds_dwordx4 v173, s[6:7]
	s_add_u32 m0, s101, 0x5000
	s_nop 0
	global_load_lds_dwordx4 v171, s[6:7]
	s_add_u32 s4, s4, 0x10000
	s_addc_u32 s5, s5, 0
	s_add_u32 s6, s6, 0x120000
	s_addc_u32 s7, s7, 0
	s_add_i32 s101, s100, 0x6000
	s_mov_b32 m0, s101
	s_nop 0
	global_load_lds_dwordx4 v170, s[4:5]
	s_add_u32 m0, s101, 0x1000
	s_nop 0
	global_load_lds_dwordx4 v171, s[4:5]
	s_add_u32 m0, s101, 0x2000
	s_nop 0
	global_load_lds_dwordx4 v172, s[6:7]
	s_add_u32 m0, s101, 0x3000
	s_nop 0
	global_load_lds_dwordx4 v170, s[6:7]
	s_add_u32 m0, s101, 0x4000
	s_nop 0
	global_load_lds_dwordx4 v173, s[6:7]
	s_add_u32 m0, s101, 0x5000
	s_nop 0
	global_load_lds_dwordx4 v171, s[6:7]
	s_add_u32 s4, s4, 0x10000
	s_addc_u32 s5, s5, 0
	s_add_u32 s6, s6, 0x120000
	s_addc_u32 s7, s7, 0
	s_mov_b32 s34, 0
	s_mov_b32 s35, 2
	s_mov_b32 s29, 29
	s_mul_i32 s40, s34, 0x6000
	s_add_i32 s40, s40, 32
	v_add_u32_e32 v135, s40, v134
	v_add_u32_e32 v168, s40, v133
	v_add_u32_e32 v194, v135, v131
	v_add_u32_e32 v195, v168, v131
	s_waitcnt vmcnt(6)
	s_waitcnt lgkmcnt(0)
	s_barrier
; #define MFMA(a, b, c) __builtin_amdgcn_mfma_f32_32x32x16_bf16((a), (b), (c), 0, 0, 0)
; #define G_ISSUE(ks_, buf_) do { \
;     const bf16_t* wq_ = wp + (ks_) * wks; const bf16_t* xq_ = xp + (ks_) * xks; char* lb_ = ld + (buf_) * STAGE; \
;     dma16(wq_, lb_); dma16(wq_ + 2048, lb_ + 4096); \
;     _Pragma("unroll") for (int i_ = 0; i_ < TJ; ++i_) dma16(xq_ + i_ * 2048, lb_ + 8192 + i_ * 4096); } while (0)
; template <bool VMODE, int TJ>
; DI void gemm_mainloop(const bf16_t* __restrict__ W, const bf16_t* __restrict__ X, int NW, char* smem, f32x16 (&acc)[2][TJ]) {
;     ...
;         for (int ks = 0; ks < 32; ++ks) {
;             if (ks < 31) asm volatile("s_waitcnt vmcnt(6)" ::: "memory");
;             else asm volatile("s_waitcnt vmcnt(0)" ::: "memory");
;             __builtin_amdgcn_s_barrier();
;             const char* sw = smem + bc * STAGE + wf * 64 * 64;
;             const char* sx = smem + bc * STAGE + 8192 + wt * (32 * TJ) * 64;
;             bf16x8 fw[2], fx[TJ], gw[2], gx[TJ];
; #pragma unroll
;             for (int i = 0; i < 2; ++i) fw[i] = *(const bf16x8*)(sw + i * 32 * 64 + fo0);
; #pragma unroll
;             for (int j = 0; j < TJ; ++j) fx[j] = *(const bf16x8*)(sx + j * 32 * 64 + fo0);
;             __builtin_amdgcn_sched_barrier(0);
;             if (ks + 2 < 32) G_ISSUE(ks + 2, bn);
;             __builtin_amdgcn_sched_barrier(0);
; #pragma unroll
;             for (int i = 0; i < 2; ++i) gw[i] = *(const bf16x8*)(sw + i * 32 * 64 + fo1);
; #pragma unroll
;             for (int j = 0; j < TJ; ++j) gx[j] = *(const bf16x8*)(sx + j * 32 * 64 + fo1);
; #pragma unroll
;             for (int i = 0; i < 2; ++i)
; #pragma unroll
;                 for (int j = 0; j < TJ; ++j) acc[i][j] = VMODE ? MFMA(fx[j], fw[i], acc[i][j]) : MFMA(fw[i], fx[j], acc[i][j]);
; #pragma unroll
;             for (int i = 0; i < 2; ++i)
; #pragma unroll
;                 for (int j = 0; j < TJ; ++j) acc[i][j] = VMODE ? MFMA(gx[j], gw[i], acc[i][j]) : MFMA(gw[i], gx[j], acc[i][j]);
;             bc = (bc == 2) ? 0 : bc + 1; bn = (bn == 2) ? 0 : bn + 1;
;         }
	ds_read_b128 v[136:139], v194
	ds_read_b128 v[140:143], v194 offset:2048
	ds_read_b128 v[144:147], v195 offset:8192
	ds_read_b128 v[148:151], v195 offset:10240
	ds_read_b128 v[152:155], v195 offset:12288
	ds_read_b128 v[156:159], v195 offset:14336
	s_mul_i32 s40, s35, 0x6000
	s_add_i32 s101, s40, s100
	s_add_i32 s40, s34, 1
	s_cmp_lg_u32 s34, 2
	s_cselect_b32 s34, s40, 0
	s_add_i32 s40, s35, 1
	s_cmp_lg_u32 s35, 2
	s_cselect_b32 s35, s40, 0
	v_add_u32_e32 v169, v135, v132
	v_add_u32_e32 v196, v168, v132
	s_mov_b32 m0, s101
	s_nop 0
	global_load_lds_dwordx4 v170, s[4:5]
	s_add_u32 m0, s101, 0x1000
	s_nop 0
	global_load_lds_dwordx4 v171, s[4:5]
	s_add_u32 m0, s101, 0x2000
	s_nop 0
	global_load_lds_dwordx4 v172, s[6:7]
	s_add_u32 m0, s101, 0x3000
	s_nop 0
	global_load_lds_dwordx4 v170, s[6:7]
	s_add_u32 m0, s101, 0x4000
	s_nop 0
	global_load_lds_dwordx4 v173, s[6:7]
	s_add_u32 m0, s101, 0x5000
	s_nop 0
	global_load_lds_dwordx4 v171, s[6:7]
	s_add_u32 s4, s4, 0x10000
	s_addc_u32 s5, s5, 0
	s_add_u32 s6, s6, 0x120000
	s_addc_u32 s7, s7, 0
	s_waitcnt lgkmcnt(0)
	v_mfma_f32_32x32x16_bf16 v[112:127], v[136:139], v[144:147], v[112:127]
	ds_read_b128 v[160:163], v169
	v_mfma_f32_32x32x16_bf16 v[96:111], v[136:139], v[148:151], v[96:111]
	ds_read_b128 v[176:179], v169 offset:2048
	v_mfma_f32_32x32x16_bf16 v[48:63], v[136:139], v[152:155], v[48:63]
	ds_read_b128 v[164:167], v196 offset:8192
	v_mfma_f32_32x32x16_bf16 v[32:47], v[136:139], v[156:159], v[32:47]
	ds_read_b128 v[180:183], v196 offset:10240
	v_mfma_f32_32x32x16_bf16 v[80:95], v[140:143], v[144:147], v[80:95]
	ds_read_b128 v[184:187], v196 offset:12288
	v_mfma_f32_32x32x16_bf16 v[64:79], v[140:143], v[148:151], v[64:79]
	ds_read_b128 v[188:191], v196 offset:14336
	v_mfma_f32_32x32x16_bf16 v[16:31], v[140:143], v[152:155], v[16:31]
	v_mfma_f32_32x32x16_bf16 v[0:15], v[140:143], v[156:159], v[0:15]
.Lop4_loop:
	s_mul_i32 s40, s34, 0x6000
	s_add_i32 s40, s40, 32
	v_add_u32_e32 v135, s40, v134
	v_add_u32_e32 v168, s40, v133
	v_add_u32_e32 v194, v135, v131
	v_add_u32_e32 v195, v168, v131
	s_waitcnt vmcnt(6)
	s_waitcnt lgkmcnt(0)
	s_barrier
	ds_read_b128 v[136:139], v194
	ds_read_b128 v[140:143], v194 offset:2048
	ds_read_b128 v[144:147], v195 offset:8192
	ds_read_b128 v[148:151], v195 offset:10240
	ds_read_b128 v[152:155], v195 offset:12288
	ds_read_b128 v[156:159], v195 offset:14336
	s_mul_i32 s40, s35, 0x6000
	s_add_i32 s101, s40, s100
	s_add_i32 s40, s34, 1
	s_cmp_lg_u32 s34, 2
	s_cselect_b32 s34, s40, 0
	s_add_i32 s40, s35, 1
	s_cmp_lg_u32 s35, 2
	s_cselect_b32 s35, s40, 0
	v_add_u32_e32 v169, v135, v132
	v_add_u32_e32 v196, v168, v132
	s_mov_b32 m0, s101
	v_mfma_f32_32x32x16_bf16 v[112:127], v[160:163], v[164:167], v[112:127]
	global_load_lds_dwordx4 v170, s[4:5]
	s_add_u32 m0, s101, 0x1000
	v_mfma_f32_32x32x16_bf16 v[96:111], v[160:163], v[180:183], v[96:111]
	global_load_lds_dwordx4 v171, s[4:5]
	s_add_u32 m0, s101, 0x2000
	v_mfma_f32_32x32x16_bf16 v[48:63], v[160:163], v[184:187], v[48:63]
	global_load_lds_dwordx4 v172, s[6:7]
	s_add_u32 m0, s101, 0x3000
	v_mfma_f32_32x32x16_bf16 v[32:47], v[160:163], v[188:191], v[32:47]
	global_load_lds_dwordx4 v170, s[6:7]
	s_add_u32 m0, s101, 0x4000
	v_mfma_f32_32x32x16_bf16 v[80:95], v[176:179], v[164:167], v[80:95]
	global_load_lds_dwordx4 v173, s[6:7]
	s_add_u32 m0, s101, 0x5000
	v_mfma_f32_32x32x16_bf16 v[64:79], v[176:179], v[180:183], v[64:79]
	global_load_lds_dwordx4 v171, s[6:7]
	s_add_u32 s4, s4, 0x10000
	s_addc_u32 s5, s5, 0
	s_add_u32 s6, s6, 0x120000
	s_addc_u32 s7, s7, 0
	v_mfma_f32_32x32x16_bf16 v[16:31], v[176:179], v[184:187], v[16:31]
	v_mfma_f32_32x32x16_bf16 v[0:15], v[176:179], v[188:191], v[0:15]
	s_waitcnt lgkmcnt(0)
	v_mfma_f32_32x32x16_bf16 v[112:127], v[136:139], v[144:147], v[112:127]
	ds_read_b128 v[160:163], v169
	v_mfma_f32_32x32x16_bf16 v[96:111], v[136:139], v[148:151], v[96:111]
	ds_read_b128 v[176:179], v169 offset:2048
	v_mfma_f32_32x32x16_bf16 v[48:63], v[136:139], v[152:155], v[48:63]
	ds_read_b128 v[164:167], v196 offset:8192
	v_mfma_f32_32x32x16_bf16 v[32:47], v[136:139], v[156:159], v[32:47]
	ds_read_b128 v[180:183], v196 offset:10240
	v_mfma_f32_32x32x16_bf16 v[80:95], v[140:143], v[144:147], v[80:95]
	ds_read_b128 v[184:187], v196 offset:12288
	v_mfma_f32_32x32x16_bf16 v[64:79], v[140:143], v[148:151], v[64:79]
	ds_read_b128 v[188:191], v196 offset:14336
	v_mfma_f32_32x32x16_bf16 v[16:31], v[140:143], v[152:155], v[16:31]
	v_mfma_f32_32x32x16_bf16 v[0:15], v[140:143], v[156:159], v[0:15]
	s_add_i32 s29, s29, -1
	s_cmp_lg_u32 s29, 0
	s_cbranch_scc1 .Lop4_loop
	s_mul_i32 s40, s34, 0x6000
	s_add_i32 s40, s40, 32
	v_add_u32_e32 v135, s40, v134
	v_add_u32_e32 v168, s40, v133
	v_add_u32_e32 v194, v135, v131
	v_add_u32_e32 v195, v168, v131
	s_waitcnt vmcnt(6)
	s_waitcnt lgkmcnt(0)
	s_barrier
; #define MFMA(a, b, c) __builtin_amdgcn_mfma_f32_32x32x16_bf16((a), (b), (c), 0, 0, 0)
; template <bool VMODE, int TJ>
; DI void gemm_mainloop(const bf16_t* __restrict__ W, const bf16_t* __restrict__ X, int NW, char* smem, f32x16 (&acc)[2][TJ]) {
;     ...
;         for (int ks = 0; ks < 32; ++ks) {
;             if (ks < 31) asm volatile("s_waitcnt vmcnt(6)" ::: "memory");
;             else asm volatile("s_waitcnt vmcnt(0)" ::: "memory");
;             __builtin_amdgcn_s_barrier();
;             const char* sw = smem + bc * STAGE + wf * 64 * 64;
;             const char* sx = smem + bc * STAGE + 8192 + wt * (32 * TJ) * 64;
;             bf16x8 fw[2], fx[TJ], gw[2], gx[TJ];
; #pragma unroll
;             for (int i = 0; i < 2; ++i) fw[i] = *(const bf16x8*)(sw + i * 32 * 64 + fo0);
; #pragma unroll
;             for (int j = 0; j < TJ; ++j) fx[j] = *(const bf16x8*)(sx + j * 32 * 64 + fo0);
;             __builtin_amdgcn_sched_barrier(0);
;             if (ks + 2 < 32) G_ISSUE(ks + 2, bn);
;             __builtin_amdgcn_sched_barrier(0);
; #pragma unroll
;             for (int i = 0; i < 2; ++i) gw[i] = *(const bf16x8*)(sw + i * 32 * 64 + fo1);
; #pragma unroll
;             for (int j = 0; j < TJ; ++j) gx[j] = *(const bf16x8*)(sx + j * 32 * 64 + fo1);
; #pragma unroll
;             for (int i = 0; i < 2; ++i)
; #pragma unroll
;                 for (int j = 0; j < TJ; ++j) acc[i][j] = VMODE ? MFMA(fx[j], fw[i], acc[i][j]) : MFMA(fw[i], fx[j], acc[i][j]);
; #pragma unroll
;             for (int i = 0; i < 2; ++i)
; #pragma unroll
;                 for (int j = 0; j < TJ; ++j) acc[i][j] = VMODE ? MFMA(gx[j], gw[i], acc[i][j]) : MFMA(gw[i], gx[j], acc[i][j]);
;             bc = (bc == 2) ? 0 : bc + 1; bn = (bn == 2) ? 0 : bn + 1;
;         }
;     }
;     ...
;     __syncthreads();
; template <int TJ>
; DI void outproj_tile(const Params& p, int l, char* smem, int b, int trow0, int n0) {
;     ...
;     const float* gt = p.mod + ((size_t)l * 9 + (trow0 < SEQ ? b : 8)) * 3072 + 2048 + n0 + 64 * wf;
;     const float* xs = src_row(p, l, b, trow0 + 32 * TJ * wt) + n0 + 64 * wf;
;     float* xd = dst_row(p, b, trow0 + 32 * TJ * wt) + n0 + 64 * wf;
	ds_read_b128 v[136:139], v194
	ds_read_b128 v[140:143], v194 offset:2048
	ds_read_b128 v[144:147], v195 offset:8192
	ds_read_b128 v[148:151], v195 offset:10240
	ds_read_b128 v[152:155], v195 offset:12288
	ds_read_b128 v[156:159], v195 offset:14336
	s_add_i32 s40, s34, 1
	s_cmp_lg_u32 s34, 2
	s_cselect_b32 s34, s40, 0
	s_add_i32 s40, s35, 1
	s_cmp_lg_u32 s35, 2
	s_cselect_b32 s35, s40, 0
	v_add_u32_e32 v169, v135, v132
	v_add_u32_e32 v196, v168, v132
	v_mfma_f32_32x32x16_bf16 v[112:127], v[160:163], v[164:167], v[112:127]
	v_mfma_f32_32x32x16_bf16 v[96:111], v[160:163], v[180:183], v[96:111]
	v_mfma_f32_32x32x16_bf16 v[48:63], v[160:163], v[184:187], v[48:63]
	v_mfma_f32_32x32x16_bf16 v[32:47], v[160:163], v[188:191], v[32:47]
	v_mfma_f32_32x32x16_bf16 v[80:95], v[176:179], v[164:167], v[80:95]
	v_mfma_f32_32x32x16_bf16 v[64:79], v[176:179], v[180:183], v[64:79]
	v_mfma_f32_32x32x16_bf16 v[16:31], v[176:179], v[184:187], v[16:31]
	v_mfma_f32_32x32x16_bf16 v[0:15], v[176:179], v[188:191], v[0:15]
	s_waitcnt lgkmcnt(0)
	v_mfma_f32_32x32x16_bf16 v[112:127], v[136:139], v[144:147], v[112:127]
	ds_read_b128 v[160:163], v169
	v_mfma_f32_32x32x16_bf16 v[96:111], v[136:139], v[148:151], v[96:111]
	ds_read_b128 v[176:179], v169 offset:2048
	v_mfma_f32_32x32x16_bf16 v[48:63], v[136:139], v[152:155], v[48:63]
	ds_read_b128 v[164:167], v196 offset:8192
	v_mfma_f32_32x32x16_bf16 v[32:47], v[136:139], v[156:159], v[32:47]
	ds_read_b128 v[180:183], v196 offset:10240
	v_mfma_f32_32x32x16_bf16 v[80:95], v[140:143], v[144:147], v[80:95]
	ds_read_b128 v[184:187], v196 offset:12288
	v_mfma_f32_32x32x16_bf16 v[64:79], v[140:143], v[148:151], v[64:79]
	ds_read_b128 v[188:191], v196 offset:14336
	v_mfma_f32_32x32x16_bf16 v[16:31], v[140:143], v[152:155], v[16:31]
	v_mfma_f32_32x32x16_bf16 v[0:15], v[140:143], v[156:159], v[0:15]
	s_mul_i32 s40, s34, 0x6000
	s_add_i32 s40, s40, 32
	v_add_u32_e32 v135, s40, v134
	v_add_u32_e32 v168, s40, v133
	v_add_u32_e32 v194, v135, v131
	v_add_u32_e32 v195, v168, v131
	s_waitcnt vmcnt(0)
	s_waitcnt lgkmcnt(0)
	s_barrier
	ds_read_b128 v[136:139], v194
	ds_read_b128 v[140:143], v194 offset:2048
	ds_read_b128 v[144:147], v195 offset:8192
	ds_read_b128 v[148:151], v195 offset:10240
	ds_read_b128 v[152:155], v195 offset:12288
	ds_read_b128 v[156:159], v195 offset:14336
	s_add_i32 s40, s34, 1
	s_cmp_lg_u32 s34, 2
	s_cselect_b32 s34, s40, 0
	s_add_i32 s40, s35, 1
	s_cmp_lg_u32 s35, 2
	s_cselect_b32 s35, s40, 0
	v_add_u32_e32 v169, v135, v132
	v_add_u32_e32 v196, v168, v132
	v_mfma_f32_32x32x16_bf16 v[112:127], v[160:163], v[164:167], v[112:127]
	v_mfma_f32_32x32x16_bf16 v[96:111], v[160:163], v[180:183], v[96:111]
	v_mfma_f32_32x32x16_bf16 v[48:63], v[160:163], v[184:187], v[48:63]
	v_mfma_f32_32x32x16_bf16 v[32:47], v[160:163], v[188:191], v[32:47]
	v_mfma_f32_32x32x16_bf16 v[80:95], v[176:179], v[164:167], v[80:95]
	v_mfma_f32_32x32x16_bf16 v[64:79], v[176:179], v[180:183], v[64:79]
	v_mfma_f32_32x32x16_bf16 v[16:31], v[176:179], v[184:187], v[16:31]
	v_mfma_f32_32x32x16_bf16 v[0:15], v[176:179], v[188:191], v[0:15]
	s_waitcnt lgkmcnt(0)
	v_mfma_f32_32x32x16_bf16 v[112:127], v[136:139], v[144:147], v[112:127]
	ds_read_b128 v[160:163], v169
	v_mfma_f32_32x32x16_bf16 v[96:111], v[136:139], v[148:151], v[96:111]
	ds_read_b128 v[176:179], v169 offset:2048
	v_mfma_f32_32x32x16_bf16 v[48:63], v[136:139], v[152:155], v[48:63]
	ds_read_b128 v[164:167], v196 offset:8192
	v_mfma_f32_32x32x16_bf16 v[32:47], v[136:139], v[156:159], v[32:47]
	ds_read_b128 v[180:183], v196 offset:10240
	v_mfma_f32_32x32x16_bf16 v[80:95], v[140:143], v[144:147], v[80:95]
	ds_read_b128 v[184:187], v196 offset:12288
	v_mfma_f32_32x32x16_bf16 v[64:79], v[140:143], v[148:151], v[64:79]
	ds_read_b128 v[188:191], v196 offset:14336
	v_mfma_f32_32x32x16_bf16 v[16:31], v[140:143], v[152:155], v[16:31]
	v_mfma_f32_32x32x16_bf16 v[0:15], v[140:143], v[156:159], v[0:15]
	s_waitcnt lgkmcnt(0)
	v_mfma_f32_32x32x16_bf16 v[112:127], v[160:163], v[164:167], v[112:127]
	v_mfma_f32_32x32x16_bf16 v[96:111], v[160:163], v[180:183], v[96:111]
	v_mfma_f32_32x32x16_bf16 v[48:63], v[160:163], v[184:187], v[48:63]
	v_mfma_f32_32x32x16_bf16 v[32:47], v[160:163], v[188:191], v[32:47]
	v_mfma_f32_32x32x16_bf16 v[80:95], v[176:179], v[164:167], v[80:95]
	v_mfma_f32_32x32x16_bf16 v[64:79], v[176:179], v[180:183], v[64:79]
	v_mfma_f32_32x32x16_bf16 v[16:31], v[176:179], v[184:187], v[16:31]
	v_mfma_f32_32x32x16_bf16 v[0:15], v[176:179], v[188:191], v[0:15]
	s_waitcnt vmcnt(0) lgkmcnt(0)
	s_barrier
	s_nop 7
	s_nop 7
	v_mov_b32_e32 v172, v64
	v_mov_b32_e32 v173, v65
	v_mov_b32_e32 v174, v66
	v_mov_b32_e32 v175, v67
	v_mov_b32_e32 v176, v68
	v_mov_b32_e32 v177, v69
	v_mov_b32_e32 v178, v70
	v_mov_b32_e32 v179, v71
	v_mov_b32_e32 v180, v72
	v_mov_b32_e32 v181, v73
	v_mov_b32_e32 v182, v74
	v_mov_b32_e32 v183, v75
	v_mov_b32_e32 v184, v76
	v_mov_b32_e32 v185, v77
	v_mov_b32_e32 v186, v78
	v_mov_b32_e32 v187, v79
	v_mov_b32_e32 v188, v80
	v_mov_b32_e32 v189, v81
	v_mov_b32_e32 v190, v82
	v_mov_b32_e32 v191, v83
	v_mov_b32_e32 v194, v84
	v_mov_b32_e32 v195, v85
	v_mov_b32_e32 v196, v86
	v_mov_b32_e32 v197, v87
	v_mov_b32_e32 v198, v88
	v_mov_b32_e32 v199, v89
	v_mov_b32_e32 v214, v90
	v_mov_b32_e32 v215, v91
	v_mov_b32_e32 v216, v92
	v_mov_b32_e32 v217, v93
	v_mov_b32_e32 v218, v94
	v_mov_b32_e32 v219, v95
	v_mov_b32_e32 v220, v96
	v_mov_b32_e32 v221, v97
	v_mov_b32_e32 v222, v98
	v_mov_b32_e32 v223, v99
	v_mov_b32_e32 v224, v100
	v_mov_b32_e32 v225, v101
	v_mov_b32_e32 v226, v102
	v_mov_b32_e32 v227, v103
	v_mov_b32_e32 v228, v104
	v_mov_b32_e32 v229, v105
	v_mov_b32_e32 v230, v106
	v_mov_b32_e32 v231, v107
	v_mov_b32_e32 v232, v108
	v_mov_b32_e32 v233, v109
	v_mov_b32_e32 v234, v110
	v_mov_b32_e32 v235, v111
	v_mov_b32_e32 v236, v112
	v_mov_b32_e32 v237, v113
	v_mov_b32_e32 v238, v114
	v_mov_b32_e32 v239, v115
	v_mov_b32_e32 v240, v116
	v_mov_b32_e32 v241, v117
	v_mov_b32_e32 v242, v118
	v_mov_b32_e32 v243, v119
	v_mov_b32_e32 v244, v120
	v_mov_b32_e32 v245, v121
	v_mov_b32_e32 v246, v122
	v_mov_b32_e32 v247, v123
	v_mov_b32_e32 v248, v124
	v_mov_b32_e32 v249, v125
	v_mov_b32_e32 v250, v126
	v_mov_b32_e32 v251, v127
	v_mov_b32_e32 v116, v200
	s_mov_b64 s[4:5], -1
	s_and_b64 vcc, exec, s[50:51]
	s_load_dwordx2 s[52:53], s[0:1], 0xe0
	v_ashrrev_i32_e32 v64, 1, v116
	v_and_b32_e32 v64, 0xffffffc0, v64
	v_add_u32_e32 v66, s28, v64
	v_cmp_gt_i32_e64 s[40:41], s61, v66
	v_cmp_lt_i32_e64 s[42:43], s21, v66
	s_branch .Lop4_epi
; template <int TJ>
; DI void outproj_tile(const Params& p, int l, char* smem, int b, int trow0, int n0) {
;     ...
;     const float* gt = p.mod + ((size_t)l * 9 + (trow0 < SEQ ? b : 8)) * 3072 + 2048 + n0 + 64 * wf;
;     const float* xs = src_row(p, l, b, trow0 + 32 * TJ * wt) + n0 + 64 * wf;
;     float* xd = dst_row(p, b, trow0 + 32 * TJ * wt) + n0 + 64 * wf;
; DI void outproj_phase(const Params& p, int l, char* smem) {
;     ...
;     if (xmap) {
; #pragma unroll 1
;         for (int it = 0; it < 2; ++it) { const int idx = it * 64 + xj; outproj_tile<2>(p, l, smem, xcd, (idx >> 3) * 128, (idx & 7) * 128); }
;         if (ctxu && xj < 32) { const int tile = xj >> 1; outproj_tile<1>(p, l, smem, xcd, SEQ + (tile >> 3) * 128 + (xj & 1) * 64, (tile & 7) * 128); }
.Lop4_second:
	s_mov_b64 s[62:63], -1
	v_readlane_b32 s4, v254, 13
	s_nop 0
	s_add_i32 s4, s6, s4
	s_and_b32 s28, s4, 0x7fffff80
	v_mov_b32_e32 v0, v172
	v_mov_b32_e32 v1, v173
	v_mov_b32_e32 v2, v174
	v_mov_b32_e32 v3, v175
	v_mov_b32_e32 v4, v176
	v_mov_b32_e32 v5, v177
	v_mov_b32_e32 v6, v178
	v_mov_b32_e32 v7, v179
	v_mov_b32_e32 v8, v180
	v_mov_b32_e32 v9, v181
	v_mov_b32_e32 v10, v182
	v_mov_b32_e32 v11, v183
	v_mov_b32_e32 v12, v184
	v_mov_b32_e32 v13, v185
	v_mov_b32_e32 v14, v186
	v_mov_b32_e32 v15, v187
	v_mov_b32_e32 v16, v188
	v_mov_b32_e32 v17, v189
	v_mov_b32_e32 v18, v190
	v_mov_b32_e32 v19, v191
	v_mov_b32_e32 v20, v194
	v_mov_b32_e32 v21, v195
	v_mov_b32_e32 v22, v196
	v_mov_b32_e32 v23, v197
	v_mov_b32_e32 v24, v198
	v_mov_b32_e32 v25, v199
	v_mov_b32_e32 v26, v214
	v_mov_b32_e32 v27, v215
	v_mov_b32_e32 v28, v216
	v_mov_b32_e32 v29, v217
	v_mov_b32_e32 v30, v218
	v_mov_b32_e32 v31, v219
	v_mov_b32_e32 v32, v220
	v_mov_b32_e32 v33, v221
	v_mov_b32_e32 v34, v222
	v_mov_b32_e32 v35, v223
	v_mov_b32_e32 v36, v224
	v_mov_b32_e32 v37, v225
	v_mov_b32_e32 v38, v226
	v_mov_b32_e32 v39, v227
	v_mov_b32_e32 v40, v228
	v_mov_b32_e32 v41, v229
	v_mov_b32_e32 v42, v230
	v_mov_b32_e32 v43, v231
	v_mov_b32_e32 v44, v232
	v_mov_b32_e32 v45, v233
	v_mov_b32_e32 v46, v234
	v_mov_b32_e32 v47, v235
	v_mov_b32_e32 v48, v236
	v_mov_b32_e32 v49, v237
	v_mov_b32_e32 v50, v238
	v_mov_b32_e32 v51, v239
	v_mov_b32_e32 v52, v240
	v_mov_b32_e32 v53, v241
	v_mov_b32_e32 v54, v242
	v_mov_b32_e32 v55, v243
	v_mov_b32_e32 v56, v244
	v_mov_b32_e32 v57, v245
	v_mov_b32_e32 v58, v246
	v_mov_b32_e32 v59, v247
	v_mov_b32_e32 v60, v248
	v_mov_b32_e32 v61, v249
	v_mov_b32_e32 v62, v250
	v_mov_b32_e32 v63, v251
	s_mov_b64 s[4:5], -1
	s_and_b64 vcc, exec, s[50:51]
	s_load_dwordx2 s[52:53], s[0:1], 0xe0
	v_ashrrev_i32_e32 v64, 1, v116
	v_and_b32_e32 v64, 0xffffffc0, v64
	v_add_u32_e32 v66, s28, v64
	v_cmp_gt_i32_e64 s[40:41], s61, v66
	v_cmp_lt_i32_e64 s[42:43], s21, v66
.Lop4_epi:
	s_cbranch_vccz .LBB0_47
	s_and_saveexec_b64 s[4:5], s[42:43]
	s_xor_b64 s[4:5], exec, s[4:5]
	v_add_u32_e32 v192, 0xfffff800, v66
	v_mov_b64_e32 v[68:69], v[192:193]
	s_or_saveexec_b64 s[4:5], s[4:5]
	v_readlane_b32 s6, v254, 7
	v_readlane_b32 s7, v254, 8
	s_nop 1
	v_mov_b64_e32 v[64:65], s[6:7]
	v_readlane_b32 s6, v255, 19
	v_readlane_b32 s7, v255, 20
	s_nop 1
	v_mov_b64_e32 v[70:71], s[6:7]
	s_xor_b64 exec, exec, s[4:5]
	s_cbranch_execz .LBB0_46
	v_readlane_b32 s6, v254, 9
	v_readlane_b32 s7, v254, 10
	v_ashrrev_i32_e32 v67, 31, v66
	v_mov_b64_e32 v[68:69], v[66:67]
	v_mov_b64_e32 v[64:65], s[6:7]
	v_readlane_b32 s6, v255, 21
	v_readlane_b32 s7, v255, 22
	s_nop 1
	v_mov_b64_e32 v[70:71], s[6:7]
